# rs_precompute split: row-sum loads issued before the first K-tile's LDS-DMA pieces, reduced and written to the LDS table after those pieces are issued (overlaps the two round trips)
# speedup vs baseline: 1.0172x; 1.0010x over previous
.LBB0_692:
	s_or_b64 exec, exec, s[0:1]
	s_waitcnt lgkmcnt(0)
	v_mov_b32_e32 v0, v181
	s_barrier
	s_cmp_eq_u32 s66, 0x100
	s_cbranch_scc0 .Lrs_orig_g0
	v_and_b32_e32 v218, 0xff, v181
	s_and_b32 s5, s2, 7
	s_lshr_b32 s9, s2, 3
	s_lshl_b32 s5, s5, 4
	s_and_b32 s10, s9, 7
	s_add_i32 s5, s5, s10
	v_lshlrev_b32_e32 v218, 6, v218
	s_lshl_b32 s11, s5, 14
	s_add_u32 s12, s68, s11
	s_addc_u32 s13, s69, 0
	s_add_u32 s98, s12, 0x20000
	s_addc_u32 s99, s13, 0
	global_load_dwordx4 v[184:187], v218, s[12:13] offset:0
	global_load_dwordx4 v[188:191], v218, s[12:13] offset:16
	global_load_dwordx4 v[192:195], v218, s[12:13] offset:32
	global_load_dwordx4 v[196:199], v218, s[12:13] offset:48
	global_load_dwordx4 v[200:203], v218, s[98:99] offset:0
	global_load_dwordx4 v[204:207], v218, s[98:99] offset:16
	global_load_dwordx4 v[208:211], v218, s[98:99] offset:32
	global_load_dwordx4 v[212:215], v218, s[98:99] offset:48
	s_branch .Lrs_join_g0

.Lrs_join_g0:
	s_cmpk_lt_i32 s2, 0xb00
	s_cselect_b64 s[0:1], -1, 0
	v_mov_b32_e32 v9, v181
	v_writelane_b32 v246, s0, 58
	s_waitcnt lgkmcnt(0)
	s_barrier
	v_writelane_b32 v246, s1, 59
	s_cmpk_gt_i32 s2, 0xaff
	v_readfirstlane_b32 s1, v9
	s_cbranch_scc1 .LBB0_712
	v_lshlrev_b32_e32 v0, 4, v9
	v_add_u32_e32 v1, 0x2000, v0
	v_ashrrev_i32_e32 v2, 31, v1
	v_lshrrev_b32_e32 v2, 22, v2
	v_add_u32_e32 v2, v1, v2
	v_ashrrev_i32_e32 v8, 10, v2
	v_mul_i32_i24_e32 v2, 0x400, v8
	v_sub_u32_e32 v1, v1, v2
	v_lshrrev_b32_e32 v2, 4, v1
	v_bitop3_b32 v1, v2, v1, 32 bitop3:0x6c
	v_ashrrev_i32_e32 v2, 31, v1
	v_lshrrev_b32_e32 v2, 26, v2
	v_add_u32_e32 v2, v1, v2
	v_lshlrev_b32_e32 v3, 3, v8
	v_ashrrev_i32_e32 v10, 6, v2
	v_and_b32_e32 v3, -16, v3
	v_add_u32_e32 v3, v10, v3
	v_and_b32_e32 v4, 3, v10
	s_mov_b32 s0, 0x1fffe0
	v_lshrrev_b32_e32 v5, 2, v3
	v_lshlrev_b32_e32 v6, 1, v3
	v_and_b32_e32 v2, 0xc0, v2
	v_and_or_b32 v4, v3, s0, v4
	v_and_b32_e32 v5, 4, v5
	v_and_b32_e32 v6, 24, v6
	v_sub_u32_e32 v1, v1, v2
	v_mov_b32_e32 v2, 1
	v_or3_b32 v4, v4, v5, v6
	v_lshlrev_b32_e32 v5, 5, v8
	v_ashrrev_i16_sdwa v1, v2, sext(v1) dst_sel:DWORD dst_unused:UNUSED_PAD src0_sel:DWORD src1_sel:BYTE_0
	v_and_b32_e32 v5, 32, v5
	v_bfe_i32 v11, v1, 0, 16
	v_add_lshl_u32 v1, v5, v11, 1
	v_lshl_add_u32 v128, v4, 11, v1
	v_lshl_add_u32 v130, v3, 11, v1
	v_bfe_i32 v1, v9, 27, 1
	v_lshrrev_b32_e32 v1, 22, v1
	v_add_u32_e32 v1, v0, v1
	v_and_b32_e32 v1, 0xfffffc00, v1
	v_sub_u32_e32 v0, v0, v1
	v_lshrrev_b32_e32 v1, 4, v0
	v_ashrrev_i32_e32 v3, 31, v9
	v_bitop3_b32 v0, v1, v0, 32 bitop3:0x6c
	v_lshrrev_b32_e32 v3, 26, v3
	v_ashrrev_i32_e32 v1, 31, v0
	v_add_u32_e32 v3, v9, v3
	v_lshrrev_b32_e32 v1, 26, v1
	v_ashrrev_i32_e32 v13, 6, v3
	v_add_u32_e32 v1, v0, v1
	v_lshlrev_b32_e32 v3, 3, v13
	v_ashrrev_i32_e32 v12, 6, v1
	v_and_b32_e32 v3, -16, v3
	s_add_u32 s26, s64, 0x980000
	v_add_u32_e32 v3, v12, v3
	v_and_b32_e32 v4, 3, v12
	s_addc_u32 s27, s65, 0
	v_and_or_b32 v4, v3, s0, v4
	s_lshr_b32 s0, s3, 29
	s_add_i32 s0, s2, s0
	s_ashr_i32 s6, s1, 6
	s_ashr_i32 s4, s0, 3
	s_and_b32 s0, s0, -8
	s_ashr_i32 s8, s1, 8
	s_lshl_b32 s28, s6, 10
	s_sub_i32 s0, s2, s0
	s_cmp_lt_i32 s0, 0
	s_movk_i32 s29, 0x161
	s_cselect_b32 s5, s29, 0x160
	s_mul_i32 s0, s5, s0
	s_add_i32 s0, s0, s4
	s_mul_hi_i32 s4, s0, 0x2e8ba2e9
	s_lshr_b32 s5, s4, 31
	s_ashr_i32 s4, s4, 5
	s_add_i32 s4, s4, s5
	s_lshl_b32 s5, s4, 3
	s_mulk_i32 s4, 0xb0
	s_sub_i32 s4, s0, s4
	s_sext_i32_i16 s0, s4
	s_bfe_u32 s0, s0, 0x3001c
	s_add_i32 s7, s4, s0
	s_sext_i32_i16 s0, s7
	s_and_b32 s7, s7, 0xfff8
	s_sub_i32 s4, s4, s7
	s_sext_i32_i16 s4, s4
	v_lshrrev_b32_e32 v5, 2, v3
	v_lshlrev_b32_e32 v6, 1, v3
	v_and_b32_e32 v1, 0xc0, v1
	s_lshr_b32 s0, s0, 3
	s_add_i32 s18, s5, s4
	v_and_b32_e32 v5, 4, v5
	v_and_b32_e32 v6, 24, v6
	v_sub_u32_e32 v0, v0, v1
	s_ashr_i32 s19, s18, 31
	s_bfe_i64 s[10:11], s[0:1], 0x100000
	v_or3_b32 v4, v4, v5, v6
	v_lshlrev_b32_e32 v5, 5, v13
	v_ashrrev_i16_sdwa v0, v2, sext(v0) dst_sel:DWORD dst_unused:UNUSED_PAD src0_sel:DWORD src1_sel:BYTE_0
	s_lshl_b64 s[4:5], s[18:19], 19
	s_lshl_b64 s[10:11], s[10:11], 19
	v_and_b32_e32 v5, 32, v5
	v_bfe_i32 v14, v0, 0, 16
	s_add_u32 s22, s26, s10
	v_add_lshl_u32 v0, v5, v14, 1
	s_addc_u32 s23, s27, s11
	s_add_i32 s19, s28, 0
	v_lshl_add_u32 v132, v4, 11, v0
	s_add_i32 m0, s19, 0x10000
	v_lshl_add_u32 v134, v3, 11, v0
	global_load_lds_dwordx4 v132, s[22:23]
	s_add_i32 m0, s19, 0x12000
	s_add_u32 s10, s22, 0x40000
	global_load_lds_dwordx4 v128, s[22:23]
	s_addc_u32 s11, s23, 0
	s_add_i32 m0, s19, 0x14000
	v_mov_b32_e32 v133, 0
	global_load_lds_dwordx4 v132, s[10:11]
	s_add_i32 m0, s19, 0x16000
	s_add_u32 s20, s74, s4
	s_addc_u32 s21, s75, s5
	s_add_i32 s30, s19, 0x2000
	global_load_lds_dwordx4 v128, s[10:11]
	s_mov_b32 m0, s19
	s_add_u32 s4, s20, 0x40000
	global_load_lds_dwordx4 v134, s[20:21]
	s_mov_b32 m0, s30
	s_addc_u32 s5, s21, 0
	s_add_i32 s31, s19, 0x4000
	global_load_lds_dwordx4 v130, s[20:21]
	s_mov_b32 m0, s31
	s_add_i32 s33, s19, 0x6000
	global_load_lds_dwordx4 v134, s[4:5]
	s_mov_b32 m0, s33
	v_mov_b32_e32 v129, v133
	global_load_lds_dwordx4 v130, s[4:5]
	s_cmp_eq_u32 s66, 0x100
	s_cbranch_scc0 .Lrs_skipb_g0
	v_lshrrev_b32_e32 v219, 8, v181
	v_and_b32_e32 v216, 0xff, v181
	v_mov_b32_e32 v217, 0x358637bd
	v_readfirstlane_b32 s98, v219
	v_lshlrev_b32_e32 v216, 2, v216
	v_lshl_add_u32 v216, v219, 10, v216
	v_add_u32_e32 v216, 0x20000, v216
	s_lshr_b32 s99, s2, 3
	s_lshl4_add_u32 s99, s98, s99
	s_lshl4_add_u32 s99, s98, s99
	s_waitcnt vmcnt(8)
	v_add_f32_e32 v220, v184, v185
	v_add_f32_e32 v218, v186, v187
	v_add_f32_e32 v220, v220, v218
	v_add_f32_e32 v221, v188, v189
	v_add_f32_e32 v218, v190, v191
	v_add_f32_e32 v221, v221, v218
	v_add_f32_e32 v222, v192, v193
	v_add_f32_e32 v218, v194, v195
	v_add_f32_e32 v222, v222, v218
	v_add_f32_e32 v223, v196, v197
	v_add_f32_e32 v218, v198, v199
	v_add_f32_e32 v223, v223, v218
	v_add_f32_e32 v220, v220, v221
	v_add_f32_e32 v220, v220, v222
	v_add_f32_e32 v220, v220, v223
	v_fmamk_f32 v220, v220, 0x3a800000, v217
	v_rsq_f32_e32 v224, v220
	v_add_f32_e32 v220, v200, v201
	v_add_f32_e32 v218, v202, v203
	v_add_f32_e32 v220, v220, v218
	v_add_f32_e32 v221, v204, v205
	v_add_f32_e32 v218, v206, v207
	v_add_f32_e32 v221, v221, v218
	v_add_f32_e32 v222, v208, v209
	v_add_f32_e32 v218, v210, v211
	v_add_f32_e32 v222, v222, v218
	v_add_f32_e32 v223, v212, v213
	v_add_f32_e32 v218, v214, v215
	v_add_f32_e32 v223, v223, v218
	v_add_f32_e32 v220, v220, v221
	v_add_f32_e32 v220, v220, v222
	v_add_f32_e32 v220, v220, v223
	v_fmamk_f32 v220, v220, 0x3a800000, v217
	v_rsq_f32_e32 v225, v220
	s_cmp_ge_i32 s99, 176
	s_cselect_b64 vcc, -1, 0
	v_cndmask_b32_e32 v218, v224, v225, vcc
	ds_write_b32 v216, v218 offset:0
	s_cmp_ge_i32 s99, 112
	s_cselect_b64 vcc, -1, 0
	v_cndmask_b32_e32 v218, v224, v225, vcc
	ds_write_b32 v216, v218 offset:2048
	s_cmp_ge_i32 s99, 48
	s_cselect_b64 vcc, -1, 0
	v_cndmask_b32_e32 v218, v224, v225, vcc
	ds_write_b32 v216, v218 offset:4096
	s_cmp_ge_i32 s99, -16
	s_cselect_b64 vcc, -1, 0
	v_cndmask_b32_e32 v218, v224, v225, vcc
	ds_write_b32 v216, v218 offset:6144
	s_cmp_ge_i32 s99, -80
	s_cselect_b64 vcc, -1, 0
	v_cndmask_b32_e32 v218, v224, v225, vcc
	ds_write_b32 v216, v218 offset:8192
	s_cmp_eq_u32 s98, 0
	s_cbranch_scc0 .Lrs_skipb_g0
	s_cmp_ge_i32 s99, -144
	s_cselect_b64 vcc, -1, 0
	v_cndmask_b32_e32 v218, v224, v225, vcc
	ds_write_b32 v216, v218 offset:10240
.Lrs_skipb_g0:
	s_waitcnt lgkmcnt(0)
	v_mov_b32_e32 v135, v133
	v_mov_b32_e32 v131, v133
	s_cmp_eq_u32 s8, 1
	s_mov_b32 s40, 0
	v_lshl_add_u64 v[6:7], s[22:23], 0, v[132:133]
	v_lshl_add_u64 v[4:5], s[22:23], 0, v[128:129]
	v_lshl_add_u64 v[0:1], s[20:21], 0, v[134:135]
	s_cselect_b64 s[4:5], -1, 0
	s_cmp_lg_u32 s8, 1
	v_lshl_add_u64 v[2:3], s[20:21], 0, v[130:131]
	s_cbranch_scc1 .LBB0_699
	s_barrier

.LBB0_868:
	s_andn2_b64 vcc, exec, s[0:1]
	s_cbranch_vccnz .LBB0_1044
	v_ashrrev_i32_e32 v1, 31, v8
	v_lshrrev_b32_e32 v1, 26, v1
	v_add_u32_e32 v1, v8, v1
	v_ashrrev_i32_e32 v9, 6, v1
	v_bfe_i32 v1, v8, 27, 1
	v_lshlrev_b32_e32 v0, 4, v8
	v_lshrrev_b32_e32 v1, 22, v1
	v_add_u32_e32 v1, v0, v1
	v_and_b32_e32 v1, 0xfffffc00, v1
	v_sub_u32_e32 v1, v0, v1
	v_lshrrev_b32_e32 v2, 4, v1
	v_bitop3_b32 v1, v2, v1, 32 bitop3:0x6c
	v_ashrrev_i32_e32 v3, 31, v1
	v_lshrrev_b32_e32 v3, 26, v3
	v_add_u32_e32 v3, v1, v3
	v_lshlrev_b32_e32 v2, 3, v9
	v_ashrrev_i32_e32 v10, 6, v3
	v_and_b32_e32 v3, 0xc0, v3
	v_and_b32_e32 v2, -16, v2
	v_sub_u32_e32 v1, v1, v3
	v_mov_b32_e32 v3, 1
	v_add_u32_e32 v2, v10, v2
	v_ashrrev_i16_sdwa v1, v3, sext(v1) dst_sel:DWORD dst_unused:UNUSED_PAD src0_sel:DWORD src1_sel:BYTE_0
	v_lshlrev_b32_e32 v4, 5, v9
	v_bfe_i32 v11, v1, 0, 16
	v_lshlrev_b32_e32 v1, 1, v2
	v_lshrrev_b32_e32 v5, 2, v2
	v_and_b32_e32 v6, 3, v10
	s_mov_b32 s1, 0x1fffe0
	v_and_b32_e32 v4, 32, v4
	v_and_b32_e32 v1, 24, v1
	v_and_b32_e32 v5, 4, v5
	v_and_or_b32 v6, v2, s1, v6
	v_or3_b32 v1, v6, v5, v1
	v_add_lshl_u32 v4, v4, v11, 1
	v_add_u32_e32 v0, 0x2000, v0
	v_lshl_add_u32 v130, v1, 11, v4
	v_ashrrev_i32_e32 v1, 31, v0
	v_lshrrev_b32_e32 v1, 22, v1
	v_add_u32_e32 v1, v0, v1
	v_ashrrev_i32_e32 v12, 10, v1
	v_mul_i32_i24_e32 v1, 0x400, v12
	v_sub_u32_e32 v0, v0, v1
	v_lshrrev_b32_e32 v1, 4, v0
	v_bitop3_b32 v0, v1, v0, 32 bitop3:0x6c
	v_lshl_add_u32 v128, v2, 11, v4
	v_ashrrev_i32_e32 v2, 31, v0
	v_lshrrev_b32_e32 v2, 26, v2
	v_add_u32_e32 v2, v0, v2
	v_lshlrev_b32_e32 v1, 3, v12
	v_ashrrev_i32_e32 v13, 6, v2
	v_and_b32_e32 v2, 0xc0, v2
	s_add_u32 s33, s64, 0x2a80000
	v_and_b32_e32 v1, -16, v1
	v_sub_u32_e32 v0, v0, v2
	s_addc_u32 s36, s65, 0
	s_ashr_i32 s0, s4, 6
	v_add_u32_e32 v1, v13, v1
	v_ashrrev_i16_sdwa v0, v3, sext(v0) dst_sel:DWORD dst_unused:UNUSED_PAD src0_sel:DWORD src1_sel:BYTE_0
	v_and_b32_e32 v3, 3, v13
	s_ashr_i32 s9, s8, 31
	s_ashr_i32 s11, s10, 31
	v_and_or_b32 v3, v1, s1, v3
	s_ashr_i32 s1, s4, 8
	s_lshl_b32 s37, s0, 10
	s_lshl_b64 s[6:7], s[8:9], 19
	s_lshl_b64 s[12:13], s[10:11], 19
	s_add_u32 s30, s33, s12
	v_lshlrev_b32_e32 v4, 5, v12
	v_bfe_i32 v14, v0, 0, 16
	v_lshlrev_b32_e32 v0, 1, v1
	v_lshrrev_b32_e32 v2, 2, v1
	s_addc_u32 s31, s36, s13
	s_add_i32 s38, s37, 0
	v_and_b32_e32 v4, 32, v4
	v_and_b32_e32 v0, 24, v0
	v_and_b32_e32 v2, 4, v2
	s_add_i32 m0, s38, 0x10000
	v_or3_b32 v0, v3, v2, v0
	v_add_lshl_u32 v2, v4, v14, 1
	global_load_lds_dwordx4 v130, s[30:31]
	s_add_i32 m0, s38, 0x12000
	v_lshl_add_u32 v134, v0, 11, v2
	s_add_u32 s12, s30, 0x40000
	global_load_lds_dwordx4 v134, s[30:31]
	s_addc_u32 s13, s31, 0
	s_add_i32 m0, s38, 0x14000
	v_lshl_add_u32 v132, v1, 11, v2
	global_load_lds_dwordx4 v130, s[12:13]
	s_add_i32 m0, s38, 0x16000
	s_add_u32 s28, s74, s6
	s_addc_u32 s29, s75, s7
	s_add_i32 s39, s38, 0x2000
	global_load_lds_dwordx4 v134, s[12:13]
	s_mov_b32 m0, s38
	s_add_u32 s6, s28, 0x40000
	global_load_lds_dwordx4 v128, s[28:29]
	s_mov_b32 m0, s39
	s_addc_u32 s7, s29, 0
	s_add_i32 s40, s38, 0x4000
	global_load_lds_dwordx4 v132, s[28:29]
	s_mov_b32 m0, s40
	s_add_i32 s41, s38, 0x6000
	global_load_lds_dwordx4 v128, s[6:7]
	s_mov_b32 m0, s41
	v_mov_b32_e32 v131, 0
	global_load_lds_dwordx4 v132, s[6:7]
	s_cmp_eq_u32 s66, 0x100
	s_cbranch_scc0 .Lrs_skipb_i1
	v_lshrrev_b32_e32 v219, 8, v181
	v_and_b32_e32 v216, 0xff, v181
	v_mov_b32_e32 v217, 0x358637bd
	v_readfirstlane_b32 s98, v219
	v_lshlrev_b32_e32 v216, 2, v216
	v_lshl_add_u32 v216, v219, 10, v216
	v_add_u32_e32 v216, 0x20000, v216
	s_lshr_b32 s99, s2, 3
	s_lshl4_add_u32 s99, s98, s99
	s_lshl4_add_u32 s99, s98, s99
	s_waitcnt vmcnt(8)
	v_add_f32_e32 v220, v184, v185
	v_add_f32_e32 v218, v186, v187
	v_add_f32_e32 v220, v220, v218
	v_add_f32_e32 v221, v188, v189
	v_add_f32_e32 v218, v190, v191
	v_add_f32_e32 v221, v221, v218
	v_add_f32_e32 v222, v192, v193
	v_add_f32_e32 v218, v194, v195
	v_add_f32_e32 v222, v222, v218
	v_add_f32_e32 v223, v196, v197
	v_add_f32_e32 v218, v198, v199
	v_add_f32_e32 v223, v223, v218
	v_add_f32_e32 v220, v220, v221
	v_add_f32_e32 v220, v220, v222
	v_add_f32_e32 v220, v220, v223
	v_fmamk_f32 v220, v220, 0x3a800000, v217
	v_rsq_f32_e32 v224, v220
	v_add_f32_e32 v220, v200, v201
	v_add_f32_e32 v218, v202, v203
	v_add_f32_e32 v220, v220, v218
	v_add_f32_e32 v221, v204, v205
	v_add_f32_e32 v218, v206, v207
	v_add_f32_e32 v221, v221, v218
	v_add_f32_e32 v222, v208, v209
	v_add_f32_e32 v218, v210, v211
	v_add_f32_e32 v222, v222, v218
	v_add_f32_e32 v223, v212, v213
	v_add_f32_e32 v218, v214, v215
	v_add_f32_e32 v223, v223, v218
	v_add_f32_e32 v220, v220, v221
	v_add_f32_e32 v220, v220, v222
	v_add_f32_e32 v220, v220, v223
	v_fmamk_f32 v220, v220, 0x3a800000, v217
	v_rsq_f32_e32 v225, v220
	s_cmp_ge_i32 s99, 80
	s_cselect_b64 vcc, -1, 0
	v_cndmask_b32_e32 v218, v224, v225, vcc
	ds_write_b32 v216, v218 offset:0
	s_cmp_ge_i32 s99, 16
	s_cselect_b64 vcc, -1, 0
	v_cndmask_b32_e32 v218, v224, v225, vcc
	ds_write_b32 v216, v218 offset:2048
	s_cmp_eq_u32 s98, 0
	s_cbranch_scc0 .Lrs_skipb_i1
	s_cmp_ge_i32 s99, -48
	s_cselect_b64 vcc, -1, 0
	v_cndmask_b32_e32 v218, v224, v225, vcc
	ds_write_b32 v216, v218 offset:4096
.Lrs_skipb_i1:
	s_waitcnt lgkmcnt(0)
	v_mov_b32_e32 v135, v131
	v_mov_b32_e32 v129, v131
	v_mov_b32_e32 v133, v131
	s_cmp_eq_u32 s1, 1
	s_mov_b32 s9, 0
	v_lshl_add_u64 v[6:7], s[30:31], 0, v[130:131]
	v_lshl_add_u64 v[4:5], s[30:31], 0, v[134:135]
	v_lshl_add_u64 v[0:1], s[28:29], 0, v[128:129]
	s_cselect_b64 s[12:13], -1, 0
	s_cmp_lg_u32 s1, 1
	v_lshl_add_u64 v[2:3], s[28:29], 0, v[132:133]
	s_cbranch_scc1 .LBB0_871
	s_barrier

.Lrs_join_g1:
	v_readlane_b32 s0, v246, 58
	v_mov_b32_e32 v9, v181
	v_readlane_b32 s1, v246, 59
	s_waitcnt lgkmcnt(0)
	s_barrier
	s_andn2_b64 vcc, exec, s[0:1]
	v_readfirstlane_b32 s1, v9
	s_cbranch_vccnz .LBB0_1386
	v_lshlrev_b32_e32 v0, 4, v9
	v_add_u32_e32 v1, 0x2000, v0
	v_ashrrev_i32_e32 v2, 31, v1
	v_lshrrev_b32_e32 v2, 22, v2
	v_add_u32_e32 v2, v1, v2
	v_ashrrev_i32_e32 v8, 10, v2
	v_mul_i32_i24_e32 v2, 0x400, v8
	v_sub_u32_e32 v1, v1, v2
	v_lshrrev_b32_e32 v2, 4, v1
	v_bitop3_b32 v1, v2, v1, 32 bitop3:0x6c
	v_ashrrev_i32_e32 v2, 31, v1
	v_lshrrev_b32_e32 v2, 26, v2
	v_add_u32_e32 v2, v1, v2
	v_lshlrev_b32_e32 v3, 3, v8
	v_ashrrev_i32_e32 v10, 6, v2
	v_and_b32_e32 v3, -16, v3
	v_add_u32_e32 v3, v10, v3
	v_and_b32_e32 v4, 3, v10
	s_mov_b32 s0, 0x1fffe0
	v_lshrrev_b32_e32 v5, 2, v3
	v_lshlrev_b32_e32 v6, 1, v3
	v_and_b32_e32 v2, 0xc0, v2
	v_and_or_b32 v4, v3, s0, v4
	v_and_b32_e32 v5, 4, v5
	v_and_b32_e32 v6, 24, v6
	v_sub_u32_e32 v1, v1, v2
	v_mov_b32_e32 v2, 1
	v_or3_b32 v4, v4, v5, v6
	v_lshlrev_b32_e32 v5, 5, v8
	v_ashrrev_i16_sdwa v1, v2, sext(v1) dst_sel:DWORD dst_unused:UNUSED_PAD src0_sel:DWORD src1_sel:BYTE_0
	v_and_b32_e32 v5, 32, v5
	v_bfe_i32 v11, v1, 0, 16
	v_add_lshl_u32 v1, v5, v11, 1
	s_waitcnt vmcnt(6)
	v_lshl_add_u32 v128, v4, 11, v1
	v_lshl_add_u32 v130, v3, 11, v1
	v_bfe_i32 v1, v9, 27, 1
	v_lshrrev_b32_e32 v1, 22, v1
	v_add_u32_e32 v1, v0, v1
	v_and_b32_e32 v1, 0xfffffc00, v1
	v_sub_u32_e32 v0, v0, v1
	v_lshrrev_b32_e32 v1, 4, v0
	v_ashrrev_i32_e32 v3, 31, v9
	v_bitop3_b32 v0, v1, v0, 32 bitop3:0x6c
	v_lshrrev_b32_e32 v3, 26, v3
	v_ashrrev_i32_e32 v1, 31, v0
	v_add_u32_e32 v3, v9, v3
	v_lshrrev_b32_e32 v1, 26, v1
	v_ashrrev_i32_e32 v13, 6, v3
	v_add_u32_e32 v1, v0, v1
	v_lshlrev_b32_e32 v3, 3, v13
	v_ashrrev_i32_e32 v12, 6, v1
	v_and_b32_e32 v3, -16, v3
	s_add_u32 s26, s64, 0x1480000
	v_add_u32_e32 v3, v12, v3
	v_and_b32_e32 v4, 3, v12
	s_addc_u32 s27, s65, 0
	v_and_or_b32 v4, v3, s0, v4
	s_lshr_b32 s0, s3, 29
	s_add_i32 s0, s2, s0
	s_ashr_i32 s6, s1, 6
	s_ashr_i32 s4, s0, 3
	s_and_b32 s0, s0, -8
	s_ashr_i32 s8, s1, 8
	s_lshl_b32 s28, s6, 10
	s_sub_i32 s0, s2, s0
	s_cmp_lt_i32 s0, 0
	s_movk_i32 s29, 0x161
	s_cselect_b32 s5, s29, 0x160
	s_mul_i32 s0, s5, s0
	s_add_i32 s0, s0, s4
	s_mul_hi_i32 s4, s0, 0x2e8ba2e9
	s_lshr_b32 s5, s4, 31
	s_ashr_i32 s4, s4, 5
	s_add_i32 s4, s4, s5
	s_lshl_b32 s5, s4, 3
	s_mulk_i32 s4, 0xb0
	s_sub_i32 s4, s0, s4
	s_sext_i32_i16 s0, s4
	s_bfe_u32 s0, s0, 0x3001c
	s_add_i32 s7, s4, s0
	s_sext_i32_i16 s0, s7
	s_and_b32 s7, s7, 0xfff8
	s_sub_i32 s4, s4, s7
	s_sext_i32_i16 s4, s4
	v_lshrrev_b32_e32 v5, 2, v3
	v_lshlrev_b32_e32 v6, 1, v3
	v_and_b32_e32 v1, 0xc0, v1
	s_lshr_b32 s0, s0, 3
	s_add_i32 s18, s5, s4
	v_and_b32_e32 v5, 4, v5
	v_and_b32_e32 v6, 24, v6
	v_sub_u32_e32 v0, v0, v1
	s_ashr_i32 s19, s18, 31
	s_bfe_i64 s[10:11], s[0:1], 0x100000
	v_or3_b32 v4, v4, v5, v6
	v_lshlrev_b32_e32 v5, 5, v13
	v_ashrrev_i16_sdwa v0, v2, sext(v0) dst_sel:DWORD dst_unused:UNUSED_PAD src0_sel:DWORD src1_sel:BYTE_0
	s_lshl_b64 s[4:5], s[18:19], 19
	s_lshl_b64 s[10:11], s[10:11], 19
	v_and_b32_e32 v5, 32, v5
	v_bfe_i32 v14, v0, 0, 16
	s_add_u32 s22, s26, s10
	v_add_lshl_u32 v0, v5, v14, 1
	s_addc_u32 s23, s27, s11
	s_add_i32 s19, s28, 0
	s_waitcnt vmcnt(4)
	v_lshl_add_u32 v132, v4, 11, v0
	s_add_i32 m0, s19, 0x10000
	v_lshl_add_u32 v134, v3, 11, v0
	global_load_lds_dwordx4 v132, s[22:23]
	s_add_i32 m0, s19, 0x12000
	s_add_u32 s10, s22, 0x40000
	global_load_lds_dwordx4 v128, s[22:23]
	s_addc_u32 s11, s23, 0
	s_add_i32 m0, s19, 0x14000
	v_mov_b32_e32 v133, 0
	global_load_lds_dwordx4 v132, s[10:11]
	s_add_i32 m0, s19, 0x16000
	s_add_u32 s20, s74, s4
	s_addc_u32 s21, s75, s5
	s_add_i32 s30, s19, 0x2000
	global_load_lds_dwordx4 v128, s[10:11]
	s_mov_b32 m0, s19
	s_add_u32 s4, s20, 0x40000
	global_load_lds_dwordx4 v134, s[20:21]
	s_mov_b32 m0, s30
	s_addc_u32 s5, s21, 0
	s_add_i32 s31, s19, 0x4000
	global_load_lds_dwordx4 v130, s[20:21]
	s_mov_b32 m0, s31
	s_add_i32 s33, s19, 0x6000
	global_load_lds_dwordx4 v134, s[4:5]
	s_mov_b32 m0, s33
	v_mov_b32_e32 v129, v133
	global_load_lds_dwordx4 v130, s[4:5]
	s_cmp_eq_u32 s66, 0x100
	s_cbranch_scc0 .Lrs_skipb_g1
	v_lshrrev_b32_e32 v219, 8, v181
	v_and_b32_e32 v216, 0xff, v181
	v_mov_b32_e32 v217, 0x358637bd
	v_readfirstlane_b32 s98, v219
	v_lshlrev_b32_e32 v216, 2, v216
	v_lshl_add_u32 v216, v219, 10, v216
	v_add_u32_e32 v216, 0x20000, v216
	s_lshr_b32 s99, s2, 3
	s_lshl4_add_u32 s99, s98, s99
	s_lshl4_add_u32 s99, s98, s99
	s_waitcnt vmcnt(8)
	v_add_f32_e32 v220, v184, v185
	v_add_f32_e32 v218, v186, v187
	v_add_f32_e32 v220, v220, v218
	v_add_f32_e32 v221, v188, v189
	v_add_f32_e32 v218, v190, v191
	v_add_f32_e32 v221, v221, v218
	v_add_f32_e32 v222, v192, v193
	v_add_f32_e32 v218, v194, v195
	v_add_f32_e32 v222, v222, v218
	v_add_f32_e32 v223, v196, v197
	v_add_f32_e32 v218, v198, v199
	v_add_f32_e32 v223, v223, v218
	v_add_f32_e32 v220, v220, v221
	v_add_f32_e32 v220, v220, v222
	v_add_f32_e32 v220, v220, v223
	v_fmamk_f32 v220, v220, 0x3a800000, v217
	v_rsq_f32_e32 v224, v220
	v_add_f32_e32 v220, v200, v201
	v_add_f32_e32 v218, v202, v203
	v_add_f32_e32 v220, v220, v218
	v_add_f32_e32 v221, v204, v205
	v_add_f32_e32 v218, v206, v207
	v_add_f32_e32 v221, v221, v218
	v_add_f32_e32 v222, v208, v209
	v_add_f32_e32 v218, v210, v211
	v_add_f32_e32 v222, v222, v218
	v_add_f32_e32 v223, v212, v213
	v_add_f32_e32 v218, v214, v215
	v_add_f32_e32 v223, v223, v218
	v_add_f32_e32 v220, v220, v221
	v_add_f32_e32 v220, v220, v222
	v_add_f32_e32 v220, v220, v223
	v_fmamk_f32 v220, v220, 0x3a800000, v217
	v_rsq_f32_e32 v225, v220
	s_cmp_ge_i32 s99, 176
	s_cselect_b64 vcc, -1, 0
	v_cndmask_b32_e32 v218, v224, v225, vcc
	ds_write_b32 v216, v218 offset:0
	s_cmp_ge_i32 s99, 112
	s_cselect_b64 vcc, -1, 0
	v_cndmask_b32_e32 v218, v224, v225, vcc
	ds_write_b32 v216, v218 offset:2048
	s_cmp_ge_i32 s99, 48
	s_cselect_b64 vcc, -1, 0
	v_cndmask_b32_e32 v218, v224, v225, vcc
	ds_write_b32 v216, v218 offset:4096
	s_cmp_ge_i32 s99, -16
	s_cselect_b64 vcc, -1, 0
	v_cndmask_b32_e32 v218, v224, v225, vcc
	ds_write_b32 v216, v218 offset:6144
	s_cmp_ge_i32 s99, -80
	s_cselect_b64 vcc, -1, 0
	v_cndmask_b32_e32 v218, v224, v225, vcc
	ds_write_b32 v216, v218 offset:8192
	s_cmp_eq_u32 s98, 0
	s_cbranch_scc0 .Lrs_skipb_g1
	s_cmp_ge_i32 s99, -144
	s_cselect_b64 vcc, -1, 0
	v_cndmask_b32_e32 v218, v224, v225, vcc
	ds_write_b32 v216, v218 offset:10240
